# lru_tile: gate weight fragments requested at item start (into unused registers) instead of after the conv barrier
# speedup vs baseline: 1.0014x; 1.0014x over previous
.LBB0_643:
	s_andn2_b64 vcc, exec, s[10:11]
	s_cbranch_vccnz .LBB0_655
	s_add_i32 s4, s91, 0xfe40
	s_and_b32 s5, s4, 0xffff
	s_mul_i32 s5, s5, 0xaaab
	s_lshr_b32 s26, s5, 18
	s_mul_i32 s5, s26, 6
	v_readlane_b32 s18, v250, 57
	v_mov_b32_e32 v39, v203
	s_sub_i32 s4, s4, s5
	s_mov_b32 s5, 64
	v_readlane_b32 s19, v250, 58
	s_load_dwordx2 s[10:11], s[18:19], s5 offset:0x0
	s_and_b32 s4, s4, 0xffff
	v_readlane_b32 s28, v249, 32
	v_readlane_b32 s29, v249, 33
	s_lshl_b32 s30, s4, 16
	s_add_u32 s28, s28, s30
	s_addc_u32 s29, s29, 0
	v_lshrrev_b32_e32 v236, 6, v39
	v_and_b32_e32 v237, 15, v39
	v_lshl_or_b32 v236, v236, 4, v237
	v_bfe_u32 v237, v39, 4, 2
	v_lshlrev_b32_e32 v237, 4, v237
	v_lshl_add_u32 v236, v236, 8, v237
	v_add_u32_e32 v238, 0x8000, v236
	global_load_dwordx4 v[204:207], v236, s[28:29]
	global_load_dwordx4 v[208:211], v238, s[28:29]
	global_load_dwordx4 v[212:215], v236, s[28:29] offset:64
	global_load_dwordx4 v[216:219], v238, s[28:29] offset:64
	global_load_dwordx4 v[220:223], v236, s[28:29] offset:128
	global_load_dwordx4 v[224:227], v238, s[28:29] offset:128
	global_load_dwordx4 v[228:231], v236, s[28:29] offset:192
	global_load_dwordx4 v[232:235], v238, s[28:29] offset:192
	s_lshl_b64 s[12:13], s[16:17], 2
	v_lshlrev_b32_e32 v0, 4, v39
	v_and_b32_e32 v38, 0x70, v0
	s_waitcnt lgkmcnt(0)
	s_add_u32 s5, s10, s12
	s_addc_u32 s11, s11, s13
	s_lshl_b32 s12, s4, 9
	s_add_u32 s10, s5, s12
	s_addc_u32 s11, s11, 0
	v_lshlrev_b32_e32 v0, 2, v38
	s_mov_b32 s5, 56
	global_load_dwordx4 v[2:5], v0, s[10:11] offset:48
	global_load_dwordx4 v[6:9], v0, s[10:11] offset:32
	global_load_dwordx4 v[10:13], v0, s[10:11] offset:16
	global_load_dwordx4 v[14:17], v0, s[10:11]
	s_load_dwordx2 s[10:11], s[18:19], s5 offset:0x0
	s_mul_i32 s13, s52, 0x3000
	v_ashrrev_i32_e32 v22, 3, v39
	v_lshl_add_u32 v40, s26, 6, v22
	v_lshlrev_b32_e32 v34, 1, v38
	s_waitcnt lgkmcnt(0)
	s_add_u32 s10, s10, s13
	s_addc_u32 s11, s11, 0
	s_add_u32 s10, s10, s12
	s_addc_u32 s11, s11, 0
	v_lshl_add_u64 v[18:19], s[10:11], 0, v[0:1]
	s_lshl_b32 s10, s4, 8
	s_add_u32 s10, s14, s10
	s_addc_u32 s11, s15, 0
	v_mov_b32_e32 v35, v1
	v_readfirstlane_b32 s5, v39
	v_lshl_add_u64 v[20:21], s[10:11], 0, v[34:35]
	v_add_u32_e32 v0, -3, v40
	v_max_i32_e32 v0, 0, v0
	v_mad_u64_u32 v[28:29], s[12:13], v0, s63, v[20:21]
	global_load_dwordx4 v[70:73], v[28:29], off offset:16
	global_load_dwordx4 v[74:77], v[28:29], off
	v_add_u32_e32 v0, -2, v40
	v_max_i32_e32 v0, 0, v0
	v_mad_u64_u32 v[28:29], s[12:13], v0, s63, v[20:21]
	global_load_dwordx4 v[78:81], v[28:29], off offset:16
	global_load_dwordx4 v[82:85], v[28:29], off
	v_add_u32_e32 v0, -1, v40
	v_max_i32_e32 v0, 0, v0
	v_mad_u64_u32 v[28:29], s[12:13], v0, s63, v[20:21]
	global_load_dwordx4 v[86:89], v[28:29], off offset:16
	global_load_dwordx4 v[90:93], v[28:29], off
	v_mad_u64_u32 v[28:29], s[12:13], v40, s63, v[20:21]
	global_load_dwordx4 v[94:97], v[28:29], off offset:16
	global_load_dwordx4 v[98:101], v[28:29], off
	s_mov_b64 s[12:13], 0x1800
	v_lshl_add_u64 v[30:31], v[18:19], 0, s[12:13]
	global_load_dwordx4 v[54:57], v[18:19], off
	global_load_dwordx4 v[50:53], v[18:19], off offset:16
	global_load_dwordx4 v[46:49], v[18:19], off offset:32
	global_load_dwordx4 v[42:45], v[18:19], off offset:48
	global_load_dwordx4 v[102:105], v[18:19], off offset:3072
	global_load_dwordx4 v[106:109], v[18:19], off offset:3088
	global_load_dwordx4 v[110:113], v[18:19], off offset:3104
	global_load_dwordx4 v[114:117], v[18:19], off offset:3120
	global_load_dwordx4 v[118:121], v[30:31], off
	global_load_dwordx4 v[122:125], v[30:31], off offset:16
	global_load_dwordx4 v[126:129], v[30:31], off offset:32
	global_load_dwordx4 v[130:133], v[30:31], off offset:48
	global_load_dwordx4 v[58:61], v[30:31], off offset:3072
	global_load_dwordx4 v[62:65], v[30:31], off offset:3088
	global_load_dwordx4 v[66:69], v[30:31], off offset:3104
	global_load_dwordx4 v[134:137], v[30:31], off offset:3120
	v_cmp_lt_i32_e32 vcc, 2, v40
	s_and_saveexec_b64 s[10:11], vcc
	s_waitcnt vmcnt(12)
	v_lshlrev_b32_e32 v32, 16, v74
	v_and_b32_e32 v33, 0xffff0000, v74
	v_pk_fma_f32 v[14:15], v[54:55], v[32:33], v[14:15]
	v_lshlrev_b32_e32 v28, 16, v75
	v_and_b32_e32 v29, 0xffff0000, v75
	v_pk_fma_f32 v[16:17], v[56:57], v[28:29], v[16:17]
	v_lshlrev_b32_e32 v24, 16, v76
	v_and_b32_e32 v25, 0xffff0000, v76
	v_pk_fma_f32 v[10:11], v[50:51], v[24:25], v[10:11]
	v_lshlrev_b32_e32 v26, 16, v77
	v_and_b32_e32 v27, 0xffff0000, v77
	v_pk_fma_f32 v[12:13], v[52:53], v[26:27], v[12:13]
	v_lshlrev_b32_e32 v32, 16, v70
	v_and_b32_e32 v33, 0xffff0000, v70
	v_pk_fma_f32 v[6:7], v[46:47], v[32:33], v[6:7]
	v_lshlrev_b32_e32 v28, 16, v71
	v_and_b32_e32 v29, 0xffff0000, v71
	v_pk_fma_f32 v[8:9], v[48:49], v[28:29], v[8:9]
	v_lshlrev_b32_e32 v24, 16, v72
	v_and_b32_e32 v25, 0xffff0000, v72
	v_pk_fma_f32 v[2:3], v[42:43], v[24:25], v[2:3]
	v_lshlrev_b32_e32 v26, 16, v73
	v_and_b32_e32 v27, 0xffff0000, v73
	v_pk_fma_f32 v[4:5], v[44:45], v[26:27], v[4:5]
	s_or_b64 exec, exec, s[10:11]
	v_cmp_lt_i32_e32 vcc, 1, v40
	s_and_saveexec_b64 s[10:11], vcc
	s_waitcnt vmcnt(8)
	v_lshlrev_b32_e32 v32, 16, v82
	v_and_b32_e32 v33, 0xffff0000, v82
	v_pk_fma_f32 v[14:15], v[102:103], v[32:33], v[14:15]
	v_lshlrev_b32_e32 v28, 16, v83
	v_and_b32_e32 v29, 0xffff0000, v83
	v_pk_fma_f32 v[16:17], v[104:105], v[28:29], v[16:17]
	v_lshlrev_b32_e32 v24, 16, v84
	v_and_b32_e32 v25, 0xffff0000, v84
	v_pk_fma_f32 v[10:11], v[106:107], v[24:25], v[10:11]
	v_lshlrev_b32_e32 v26, 16, v85
	v_and_b32_e32 v27, 0xffff0000, v85
	v_pk_fma_f32 v[12:13], v[108:109], v[26:27], v[12:13]
	v_lshlrev_b32_e32 v32, 16, v78
	v_and_b32_e32 v33, 0xffff0000, v78
	v_pk_fma_f32 v[6:7], v[110:111], v[32:33], v[6:7]
	v_lshlrev_b32_e32 v28, 16, v79
	v_and_b32_e32 v29, 0xffff0000, v79
	v_pk_fma_f32 v[8:9], v[112:113], v[28:29], v[8:9]
	v_lshlrev_b32_e32 v24, 16, v80
	v_and_b32_e32 v25, 0xffff0000, v80
	v_pk_fma_f32 v[2:3], v[114:115], v[24:25], v[2:3]
	v_lshlrev_b32_e32 v26, 16, v81
	v_and_b32_e32 v27, 0xffff0000, v81
	v_pk_fma_f32 v[4:5], v[116:117], v[26:27], v[4:5]
	s_or_b64 exec, exec, s[10:11]
	v_cmp_lt_i32_e32 vcc, 0, v40
	s_and_saveexec_b64 s[10:11], vcc
	s_waitcnt vmcnt(4)
	v_lshlrev_b32_e32 v32, 16, v90
	v_and_b32_e32 v33, 0xffff0000, v90
	v_pk_fma_f32 v[14:15], v[118:119], v[32:33], v[14:15]
	v_lshlrev_b32_e32 v28, 16, v91
	v_and_b32_e32 v29, 0xffff0000, v91
	v_pk_fma_f32 v[16:17], v[120:121], v[28:29], v[16:17]
	v_lshlrev_b32_e32 v24, 16, v92
	v_and_b32_e32 v25, 0xffff0000, v92
	v_pk_fma_f32 v[10:11], v[122:123], v[24:25], v[10:11]
	v_lshlrev_b32_e32 v26, 16, v93
	v_and_b32_e32 v27, 0xffff0000, v93
	v_pk_fma_f32 v[12:13], v[124:125], v[26:27], v[12:13]
	v_lshlrev_b32_e32 v32, 16, v86
	v_and_b32_e32 v33, 0xffff0000, v86
	v_pk_fma_f32 v[6:7], v[126:127], v[32:33], v[6:7]
	v_lshlrev_b32_e32 v28, 16, v87
	v_and_b32_e32 v29, 0xffff0000, v87
	v_pk_fma_f32 v[8:9], v[128:129], v[28:29], v[8:9]
	v_lshlrev_b32_e32 v24, 16, v88
	v_and_b32_e32 v25, 0xffff0000, v88
	v_pk_fma_f32 v[2:3], v[130:131], v[24:25], v[2:3]
	v_lshlrev_b32_e32 v26, 16, v89
	v_and_b32_e32 v27, 0xffff0000, v89
	v_pk_fma_f32 v[4:5], v[132:133], v[26:27], v[4:5]
	s_or_b64 exec, exec, s[10:11]
	s_lshl_b32 s68, s4, 7
	v_cmp_lt_i32_e32 vcc, -1, v40
	s_and_saveexec_b64 s[10:11], vcc
	s_waitcnt vmcnt(0)
	v_lshlrev_b32_e32 v32, 16, v98
	v_and_b32_e32 v33, 0xffff0000, v98
	v_pk_fma_f32 v[14:15], v[58:59], v[32:33], v[14:15]
	v_lshlrev_b32_e32 v28, 16, v99
	v_and_b32_e32 v29, 0xffff0000, v99
	v_pk_fma_f32 v[16:17], v[60:61], v[28:29], v[16:17]
	v_lshlrev_b32_e32 v24, 16, v100
	v_and_b32_e32 v25, 0xffff0000, v100
	v_pk_fma_f32 v[10:11], v[62:63], v[24:25], v[10:11]
	v_lshlrev_b32_e32 v26, 16, v101
	v_and_b32_e32 v27, 0xffff0000, v101
	v_pk_fma_f32 v[12:13], v[64:65], v[26:27], v[12:13]
	v_lshlrev_b32_e32 v32, 16, v94
	v_and_b32_e32 v33, 0xffff0000, v94
	v_pk_fma_f32 v[6:7], v[66:67], v[32:33], v[6:7]
	v_lshlrev_b32_e32 v28, 16, v95
	v_and_b32_e32 v29, 0xffff0000, v95
	v_pk_fma_f32 v[8:9], v[68:69], v[28:29], v[8:9]
	v_lshlrev_b32_e32 v24, 16, v96
	v_and_b32_e32 v25, 0xffff0000, v96
	v_pk_fma_f32 v[2:3], v[134:135], v[24:25], v[2:3]
	v_lshlrev_b32_e32 v26, 16, v97
	v_and_b32_e32 v27, 0xffff0000, v97
	v_pk_fma_f32 v[4:5], v[136:137], v[26:27], v[4:5]
	s_or_b64 exec, exec, s[10:11]
.LBB0_650:
	s_or_b64 exec, exec, s[10:11]
	s_lshl_b32 s4, s4, 16
	v_readlane_b32 s10, v249, 32
	s_add_u32 s10, s10, s4
	v_readlane_b32 s4, v249, 33
	s_addc_u32 s11, s4, 0
	s_ashr_i32 s4, s5, 2
	s_and_b32 s5, s4, -16
	v_and_b32_e32 v18, 15, v39
	v_bfi_b32 v36, -16, s4, v39
	s_addk_i32 s5, 0x80
	s_waitcnt vmcnt(2)
	v_cvt_pk_bf16_f32 v6, v6, v7
	v_cvt_pk_bf16_f32 v7, v8, v9
	v_cvt_pk_bf16_f32 v9, v4, v5
	v_ashrrev_i32_e32 v37, 31, v36
	v_or_b32_e32 v4, s5, v18
	v_cvt_pk_bf16_f32 v8, v2, v3
	s_movk_i32 s18, 0x110
	v_bfe_u32 v44, v39, 4, 2
	v_lshlrev_b64 v[2:3], 8, v[36:37]
	v_ashrrev_i32_e32 v5, 31, v4
	v_mul_lo_u32 v41, v22, s18
	v_lshl_add_u64 v[2:3], s[10:11], 0, v[2:3]
	v_lshlrev_b32_e32 v0, 4, v44
	v_lshlrev_b64 v[4:5], 8, v[4:5]
	s_waitcnt vmcnt(0)
	v_cvt_pk_bf16_f32 v14, v14, v15
	v_cvt_pk_bf16_f32 v15, v16, v17
	v_cvt_pk_bf16_f32 v16, v10, v11
	v_cvt_pk_bf16_f32 v17, v12, v13
	v_add3_u32 v35, 0, v41, v34
	v_lshl_add_u64 v[2:3], v[2:3], 0, v[0:1]
	v_lshl_add_u64 v[4:5], s[10:11], 0, v[4:5]
	ds_write_b128 v35, v[14:17]
	ds_write_b128 v35, v[6:9] offset:16
	s_waitcnt lgkmcnt(0)
	s_barrier
	v_lshl_add_u64 v[4:5], v[4:5], 0, v[0:1]
	v_mul_u32_u24_e32 v14, 0x110, v18
	v_add3_u32 v45, 0, v0, v14
	v_readlane_b32 s12, v250, 57
	v_readlane_b32 s13, v250, 58
	s_add_i32 s10, s68, s16
	v_add_u32_e32 v42, s10, v36
	v_ashrrev_i32_e32 v43, 31, v42
	v_lshlrev_b64 v[46:47], 2, v[42:43]
	s_movk_i32 s4, 0x50
	s_movk_i32 s10, 0x60
	s_load_dwordx2 s[4:5], s[12:13], s4 offset:0x0
	s_load_dwordx2 s[10:11], s[12:13], s10 offset:0x0
	s_waitcnt lgkmcnt(0)
	v_lshl_add_u64 v[42:43], s[4:5], 0, v[46:47]
	global_load_dword v37, v[42:43], off
	v_lshl_add_u64 v[42:43], s[10:11], 0, v[46:47]
	s_movk_i32 s4, 0x68
	global_load_dword v42, v[42:43], off
	s_load_dwordx2 s[4:5], s[12:13], s4 offset:0x0
	s_waitcnt lgkmcnt(0)
	v_lshl_add_u64 v[46:47], s[4:5], 0, v[46:47]
	global_load_dword v0, v[46:47], off
	ds_read_b128 v[102:105], v45
	ds_read_b128 v[106:109], v45 offset:4352
	ds_read_b128 v[110:113], v45 offset:8704
	ds_read_b128 v[114:117], v45 offset:13056
	ds_read_b128 v[118:121], v45 offset:64
	ds_read_b128 v[122:125], v45 offset:4416
	ds_read_b128 v[126:129], v45 offset:8768
	ds_read_b128 v[130:133], v45 offset:13120
	ds_read_b128 v[134:137], v45 offset:128
	ds_read_b128 v[50:53], v45 offset:4480
	ds_read_b128 v[54:57], v45 offset:8832
	ds_read_b128 v[58:61], v45 offset:13184
	ds_read_b128 v[62:65], v45 offset:192
	ds_read_b128 v[66:69], v45 offset:4544
	ds_read_b128 v[46:49], v45 offset:8896
	s_waitcnt vmcnt(9)
	s_waitcnt lgkmcnt(14)
	v_mfma_f32_16x16x32_bf16 v[30:33], v[102:105], v[204:207], 0
	v_mfma_f32_16x16x32_bf16 v[26:29], v[102:105], v[208:211], 0
	s_waitcnt lgkmcnt(13)
	v_mfma_f32_16x16x32_bf16 v[22:25], v[106:109], v[204:207], 0
	v_mfma_f32_16x16x32_bf16 v[18:21], v[106:109], v[208:211], 0
	s_waitcnt lgkmcnt(12)
	v_mfma_f32_16x16x32_bf16 v[14:17], v[110:113], v[204:207], 0
	v_mfma_f32_16x16x32_bf16 v[10:13], v[110:113], v[208:211], 0
	s_waitcnt lgkmcnt(11)
	v_mfma_f32_16x16x32_bf16 v[6:9], v[114:117], v[204:207], 0
	v_mfma_f32_16x16x32_bf16 v[2:5], v[114:117], v[208:211], 0
	ds_read_b128 v[102:105], v45 offset:13248
	s_waitcnt vmcnt(7)
	s_waitcnt lgkmcnt(11)
	v_mfma_f32_16x16x32_bf16 v[30:33], v[118:121], v[212:215], v[30:33]
	v_mfma_f32_16x16x32_bf16 v[26:29], v[118:121], v[216:219], v[26:29]
	s_waitcnt lgkmcnt(10)
	v_mfma_f32_16x16x32_bf16 v[22:25], v[122:125], v[212:215], v[22:25]
	v_mfma_f32_16x16x32_bf16 v[18:21], v[122:125], v[216:219], v[18:21]
	s_waitcnt lgkmcnt(9)
	v_mfma_f32_16x16x32_bf16 v[14:17], v[126:129], v[212:215], v[14:17]
	v_mfma_f32_16x16x32_bf16 v[10:13], v[126:129], v[216:219], v[10:13]
	s_waitcnt lgkmcnt(8)
	v_mfma_f32_16x16x32_bf16 v[6:9], v[130:133], v[212:215], v[6:9]
	v_mfma_f32_16x16x32_bf16 v[2:5], v[130:133], v[216:219], v[2:5]
	s_waitcnt vmcnt(5)
	s_waitcnt lgkmcnt(7)
	v_mfma_f32_16x16x32_bf16 v[30:33], v[134:137], v[220:223], v[30:33]
	v_mfma_f32_16x16x32_bf16 v[26:29], v[134:137], v[224:227], v[26:29]
	s_waitcnt lgkmcnt(6)
	v_mfma_f32_16x16x32_bf16 v[22:25], v[50:53], v[220:223], v[22:25]
	v_mfma_f32_16x16x32_bf16 v[18:21], v[50:53], v[224:227], v[18:21]
	s_waitcnt lgkmcnt(5)
	v_mfma_f32_16x16x32_bf16 v[14:17], v[54:57], v[220:223], v[14:17]
	v_mfma_f32_16x16x32_bf16 v[10:13], v[54:57], v[224:227], v[10:13]
	s_waitcnt lgkmcnt(4)
	v_mfma_f32_16x16x32_bf16 v[6:9], v[58:61], v[220:223], v[6:9]
	v_mfma_f32_16x16x32_bf16 v[2:5], v[58:61], v[224:227], v[2:5]
	s_waitcnt vmcnt(3)
	s_waitcnt lgkmcnt(3)
	v_mfma_f32_16x16x32_bf16 v[30:33], v[62:65], v[228:231], v[30:33]
	v_mfma_f32_16x16x32_bf16 v[26:29], v[62:65], v[232:235], v[26:29]
	s_waitcnt lgkmcnt(2)
	v_mfma_f32_16x16x32_bf16 v[22:25], v[66:69], v[228:231], v[22:25]
	v_mfma_f32_16x16x32_bf16 v[18:21], v[66:69], v[232:235], v[18:21]
	s_waitcnt lgkmcnt(1)
	v_mfma_f32_16x16x32_bf16 v[14:17], v[46:49], v[228:231], v[14:17]
	v_mfma_f32_16x16x32_bf16 v[10:13], v[46:49], v[232:235], v[10:13]
	s_waitcnt lgkmcnt(0)
	v_mfma_f32_16x16x32_bf16 v[6:9], v[102:105], v[228:231], v[6:9]
	v_mfma_f32_16x16x32_bf16 v[2:5], v[102:105], v[232:235], v[2:5]
	s_mov_b32 s4, 0x3f2aaaab
	s_mov_b32 s5, 0xf800000
	s_waitcnt vmcnt(2)
	v_add_f32_e32 v30, v30, v37
	v_mul_f32_e32 v30, 0xbfb8aa3b, v30
	v_exp_f32_e32 v30, v30
	v_add_f32_e32 v22, v22, v37
	v_mul_f32_e32 v22, 0xbfb8aa3b, v22
	v_exp_f32_e32 v22, v22
	v_add_f32_e32 v30, 1.0, v30
	v_rcp_f32_e32 v30, v30
	v_add_f32_e32 v23, v23, v37
	s_waitcnt vmcnt(1)
	v_add_f32_e32 v26, v26, v42
	v_mul_f32_e32 v26, 0xbfb8aa3b, v26
	v_mul_f32_e32 v30, 0xc1000000, v30
	v_exp_f32_e32 v26, v26
	v_add_f32_e32 v27, v27, v42
	v_mul_f32_e32 v27, 0xbfb8aa3b, v27
	v_exp_f32_e32 v27, v27
	v_add_f32_e32 v26, 1.0, v26
	s_waitcnt vmcnt(0)
	v_mul_f32_e32 v0, 0xbfb8aa3b, v0
	v_exp_f32_e32 v0, v0
	v_rcp_f32_e32 v26, v26
	v_add_f32_e32 v27, 1.0, v27
	v_rcp_f32_e32 v27, v27
	v_add_f32_e32 v43, 1.0, v0
	v_add_f32_e32 v45, -1.0, v43
	v_sub_f32_e32 v46, v45, v43
	v_add_f32_e32 v46, 1.0, v46
	v_sub_f32_e32 v45, v0, v45
	v_add_f32_e32 v45, v45, v46
	v_frexp_mant_f32_e32 v46, v43
	v_cmp_gt_f32_e32 vcc, s4, v46
	v_cvt_f64_f32_e32 v[46:47], v43
	v_frexp_exp_i32_f64_e32 v46, v[46:47]
	v_subbrev_co_u32_e32 v46, vcc, 0, v46, vcc
	v_sub_u32_e32 v47, 0, v46
	v_ldexp_f32 v43, v43, v47
	v_ldexp_f32 v45, v45, v47
	v_add_f32_e32 v47, -1.0, v43
	v_add_f32_e32 v48, 1.0, v47
	v_sub_f32_e32 v48, v43, v48
	v_add_f32_e32 v48, v45, v48
	v_add_f32_e32 v49, v47, v48
	v_sub_f32_e32 v47, v49, v47
	v_sub_f32_e32 v47, v48, v47
	v_add_f32_e32 v48, 1.0, v43
	v_add_f32_e32 v50, -1.0, v48
	v_sub_f32_e32 v43, v43, v50
	v_add_f32_e32 v43, v45, v43
	v_add_f32_e32 v45, v48, v43
	v_sub_f32_e32 v48, v45, v48
	v_sub_f32_e32 v43, v43, v48
	v_rcp_f32_e32 v48, v45
	v_cvt_f32_i32_e32 v46, v46
	s_mov_b32 s4, 0x3f317218
	v_add_f32_e32 v28, v28, v42
	v_mul_f32_e32 v50, v49, v48
	v_mul_f32_e32 v51, v45, v50
	v_fma_f32 v52, v50, v45, -v51
	v_fmac_f32_e32 v52, v50, v43
	v_add_f32_e32 v53, v51, v52
	v_sub_f32_e32 v54, v49, v53
	v_sub_f32_e32 v49, v49, v54
	v_sub_f32_e32 v51, v53, v51
	v_sub_f32_e32 v49, v49, v53
	v_add_f32_e32 v47, v47, v49
	v_sub_f32_e32 v49, v51, v52
	v_add_f32_e32 v47, v49, v47
	v_add_f32_e32 v49, v54, v47
	v_mul_f32_e32 v51, v48, v49
	v_mul_f32_e32 v52, v45, v51
	v_fma_f32 v45, v51, v45, -v52
	v_fmac_f32_e32 v45, v51, v43
	v_sub_f32_e32 v43, v54, v49
	v_add_f32_e32 v43, v47, v43
	v_add_f32_e32 v47, v52, v45
	v_sub_f32_e32 v53, v49, v47
	v_sub_f32_e32 v49, v49, v53
	v_sub_f32_e32 v52, v47, v52
	v_sub_f32_e32 v47, v49, v47
	v_add_f32_e32 v43, v43, v47
	v_sub_f32_e32 v45, v52, v45
	v_add_f32_e32 v43, v45, v43
	v_add_f32_e32 v45, v50, v51
	v_add_f32_e32 v43, v53, v43
	v_sub_f32_e32 v47, v45, v50
	v_mul_f32_e32 v43, v48, v43
	v_sub_f32_e32 v47, v51, v47
	v_add_f32_e32 v43, v47, v43
	v_mul_f32_e32 v50, 0x3f317218, v46
	v_add_f32_e32 v47, v45, v43
	v_fma_f32 v51, v46, s4, -v50
	v_mul_f32_e32 v48, v47, v47
	v_fmac_f32_e32 v51, 0xb102e308, v46
	v_sub_f32_e32 v45, v47, v45
	v_fmamk_f32 v49, v48, 0x3e9b6dac, v195
	v_sub_f32_e32 v43, v43, v45
	v_add_f32_e32 v45, v50, v51
	v_fmaak_f32 v49, v48, v49, 0x3f2aaada
	v_sub_f32_e32 v46, v45, v50
	v_ldexp_f32 v50, v47, 1
	v_mul_f32_e32 v47, v47, v48
	v_mul_f32_e32 v47, v47, v49
	v_add_f32_e32 v48, v50, v47
	v_sub_f32_e32 v49, v48, v50
	v_ldexp_f32 v43, v43, 1
	v_sub_f32_e32 v47, v47, v49
	v_add_f32_e32 v43, v43, v47
	v_add_f32_e32 v47, v48, v43
	v_sub_f32_e32 v48, v47, v48
	v_sub_f32_e32 v43, v43, v48
	v_add_f32_e32 v48, v45, v47
	v_sub_f32_e32 v49, v48, v45
	v_sub_f32_e32 v50, v48, v49
	v_sub_f32_e32 v46, v51, v46
	v_sub_f32_e32 v45, v45, v50
	v_sub_f32_e32 v47, v47, v49
	v_add_f32_e32 v45, v47, v45
	v_add_f32_e32 v47, v46, v43
	v_sub_f32_e32 v49, v47, v46
	v_sub_f32_e32 v50, v47, v49
	v_sub_f32_e32 v46, v46, v50
	v_sub_f32_e32 v43, v43, v49
	v_add_f32_e32 v45, v47, v45
	v_add_f32_e32 v43, v43, v46
	v_add_f32_e32 v46, v48, v45
	v_sub_f32_e32 v47, v46, v48
	v_sub_f32_e32 v45, v45, v47
	v_add_f32_e32 v43, v43, v45
	s_mov_b32 s4, 0x7f800000
	v_add_f32_e32 v43, v46, v43
	v_cmp_neq_f32_e32 vcc, s4, v0
	s_mov_b32 s4, 0x33800000
	v_mul_f32_e32 v28, 0xbfb8aa3b, v28
	v_cndmask_b32_e32 v43, v198, v43, vcc
	v_cmp_ngt_f32_e32 vcc, -1.0, v0
	v_exp_f32_e32 v28, v28
	v_add_f32_e32 v18, v18, v42
	v_cndmask_b32_e32 v43, v199, v43, vcc
	v_cmp_neq_f32_e32 vcc, -1.0, v0
	v_add_f32_e32 v28, 1.0, v28
	v_rcp_f32_e32 v28, v28
	v_cndmask_b32_e32 v43, v200, v43, vcc
	v_cmp_lt_f32_e64 vcc, |v0|, s4
	s_movk_i32 s4, 0x440
	v_mul_f32_e32 v18, 0xbfb8aa3b, v18
	v_cndmask_b32_e32 v43, v43, v0, vcc
	v_mul_f32_e32 v30, v30, v43
	v_mul_f32_e32 v30, 0x3fb8aa3b, v30
	v_exp_f32_e32 v30, v30
	v_lshl_add_u32 v0, v36, 1, 0
	v_add_f32_e32 v22, 1.0, v22
	v_exp_f32_e32 v18, v18
	v_fma_f32 v45, -v30, v30, 1.0
	v_max_f32_e32 v45, 0, v45
	v_cmp_gt_f32_e32 vcc, s5, v45
	v_mul_f32_e32 v46, 0x4f800000, v45
	v_rcp_f32_e32 v22, v22
	v_cndmask_b32_e32 v45, v45, v46, vcc
	v_sqrt_f32_e32 v46, v45
	v_add_f32_e32 v18, 1.0, v18
	v_mul_f32_e32 v23, 0xbfb8aa3b, v23
	v_exp_f32_e32 v23, v23
	v_add_u32_e32 v47, -1, v46
	v_fma_f32 v48, -v47, v46, v45
	v_cmp_ge_f32_e64 s[10:11], 0, v48
	v_add_u32_e32 v48, 1, v46
	v_add_f32_e32 v23, 1.0, v23
	v_cndmask_b32_e64 v47, v46, v47, s[10:11]
	v_fma_f32 v46, -v48, v46, v45
	v_cmp_lt_f32_e64 s[10:11], 0, v46
	v_rcp_f32_e32 v23, v23
	v_add_f32_e32 v19, v19, v42
	v_cndmask_b32_e64 v46, v47, v48, s[10:11]
	v_mul_f32_e32 v47, 0x37800000, v46
	v_cndmask_b32_e32 v46, v46, v47, vcc
	v_cmp_class_f32_e32 vcc, v45, v196
	v_mul_f32_e32 v23, 0xc1000000, v23
	v_mul_f32_e32 v23, v23, v43
	v_cndmask_b32_e32 v45, v46, v45, vcc
	v_mad_u32_u24 v46, v44, s4, v0
	ds_read_u16 v46, v46
	s_movk_i32 s4, 0x204
	v_mad_u32_u24 v47, v44, s4, v36
	v_mul_f32_e32 v26, v26, v45
	v_lshl_add_u32 v47, v47, 2, 0
	s_waitcnt lgkmcnt(0)
	v_lshlrev_b32_e32 v46, 16, v46
	v_mul_f32_e32 v26, v26, v46
	ds_write2st64_b32 v47, v30, v26 offset0:68 offset1:197
	v_add_f32_e32 v26, v31, v37
	v_mul_f32_e32 v26, 0xbfb8aa3b, v26
	v_exp_f32_e32 v26, v26
	v_lshl_or_b32 v30, v44, 2, 1
	s_movk_i32 s4, 0x81
	v_mul_f32_e32 v23, 0x3fb8aa3b, v23
	v_add_f32_e32 v26, 1.0, v26
	v_rcp_f32_e32 v26, v26
	v_exp_f32_e32 v23, v23
	v_mul_f32_e32 v19, 0xbfb8aa3b, v19
	v_exp_f32_e32 v19, v19
	v_mul_f32_e32 v26, 0xc1000000, v26
	v_mul_f32_e32 v26, v26, v43
	v_mul_f32_e32 v26, 0x3fb8aa3b, v26
	v_exp_f32_e32 v31, v26
	v_add_f32_e32 v19, 1.0, v19
	v_rcp_f32_e32 v19, v19
	v_add_f32_e32 v20, v20, v42
	v_fma_f32 v26, -v31, v31, 1.0
	v_max_f32_e32 v26, 0, v26
	v_cmp_gt_f32_e32 vcc, s5, v26
	v_mul_f32_e32 v44, 0x4f800000, v26
	v_mul_f32_e32 v20, 0xbfb8aa3b, v20
	v_cndmask_b32_e32 v26, v26, v44, vcc
	v_sqrt_f32_e32 v44, v26
	v_exp_f32_e32 v20, v20
	v_add_f32_e32 v21, v21, v42
	v_mul_f32_e32 v21, 0xbfb8aa3b, v21
	v_add_u32_e32 v45, -1, v44
	v_fma_f32 v46, -v45, v44, v26
	v_cmp_ge_f32_e64 s[10:11], 0, v46
	v_add_u32_e32 v46, 1, v44
	v_add_f32_e32 v20, 1.0, v20
	v_cndmask_b32_e64 v45, v44, v45, s[10:11]
	v_fma_f32 v44, -v46, v44, v26
	v_cmp_lt_f32_e64 s[10:11], 0, v44
	v_rcp_f32_e32 v20, v20
	v_exp_f32_e32 v21, v21
	v_cndmask_b32_e64 v44, v45, v46, s[10:11]
	v_mul_f32_e32 v45, 0x37800000, v44
	v_cndmask_b32_e32 v44, v44, v45, vcc
	v_cmp_class_f32_e32 vcc, v26, v196
	v_add_f32_e32 v14, v14, v37
	v_mul_f32_e32 v14, 0xbfb8aa3b, v14
	v_cndmask_b32_e32 v44, v44, v26, vcc
	v_mad_u32_u24 v26, v30, s18, v0
	ds_read_u16 v0, v26
	v_mul_f32_e32 v27, v27, v44
	v_exp_f32_e32 v14, v14
	v_add_f32_e32 v21, 1.0, v21
	v_add_f32_e32 v10, v10, v42
	s_waitcnt lgkmcnt(0)
	v_lshlrev_b32_e32 v45, 16, v0
	v_mad_u32_u24 v0, v30, s4, v36
	v_add_f32_e32 v30, v32, v37
	v_mul_f32_e32 v30, 0xbfb8aa3b, v30
	v_exp_f32_e32 v30, v30
	v_mul_f32_e32 v27, v27, v45
	v_lshl_add_u32 v0, v0, 2, 0
	v_rcp_f32_e32 v21, v21
	v_add_f32_e32 v30, 1.0, v30
	v_rcp_f32_e32 v30, v30
	v_mul_f32_e32 v10, 0xbfb8aa3b, v10
	v_add_f32_e32 v14, 1.0, v14
	v_exp_f32_e32 v10, v10
	v_mul_f32_e32 v30, 0xc1000000, v30
	v_mul_f32_e32 v30, v30, v43
	v_mul_f32_e32 v30, 0x3fb8aa3b, v30
	v_exp_f32_e32 v30, v30
	v_rcp_f32_e32 v14, v14
	v_add_f32_e32 v10, 1.0, v10
	v_add_f32_e32 v15, v15, v37
	v_fma_f32 v32, -v30, v30, 1.0
	v_max_f32_e32 v32, 0, v32
	v_cmp_gt_f32_e32 vcc, s5, v32
	v_mul_f32_e32 v36, 0x4f800000, v32
	v_mul_f32_e32 v15, 0xbfb8aa3b, v15
	v_cndmask_b32_e32 v32, v32, v36, vcc
	v_sqrt_f32_e32 v36, v32
	v_exp_f32_e32 v15, v15
	v_add_f32_e32 v11, v11, v42
	v_mul_f32_e32 v11, 0xbfb8aa3b, v11
	v_add_u32_e32 v44, -1, v36
	v_fma_f32 v45, -v44, v36, v32
	v_cmp_ge_f32_e64 s[10:11], 0, v45
	v_add_u32_e32 v45, 1, v36
	v_add_f32_e32 v15, 1.0, v15
	v_cndmask_b32_e64 v44, v36, v44, s[10:11]
	v_fma_f32 v36, -v45, v36, v32
	v_cmp_lt_f32_e64 s[10:11], 0, v36
	v_rcp_f32_e32 v15, v15
	v_exp_f32_e32 v11, v11
	v_cndmask_b32_e64 v36, v44, v45, s[10:11]
	v_mul_f32_e32 v44, 0x37800000, v36
	v_cndmask_b32_e32 v36, v36, v44, vcc
	v_cmp_class_f32_e32 vcc, v32, v196
	v_add_u32_e32 v44, 0x4400, v0
	ds_write2_b32 v44, v31, v30 offset1:129
	v_cndmask_b32_e32 v32, v36, v32, vcc
	ds_read_u16 v36, v26 offset:272
	v_mul_f32_e32 v28, v28, v32
	v_add_u32_e32 v30, 0xc400, v0
	v_mul_f32_e32 v15, 0xc1000000, v15
	v_mul_f32_e32 v15, v15, v43
	s_waitcnt lgkmcnt(0)
	v_lshlrev_b32_e32 v36, 16, v36
	v_mul_f32_e32 v28, v28, v36
	ds_write2_b32 v30, v27, v28 offset0:64 offset1:193
	v_add_f32_e32 v27, v33, v37
	v_mul_f32_e32 v27, 0xbfb8aa3b, v27
	v_exp_f32_e32 v27, v27
	v_add_f32_e32 v28, v29, v42
	v_mul_f32_e32 v28, 0xbfb8aa3b, v28
	v_exp_f32_e32 v28, v28
	v_add_f32_e32 v27, 1.0, v27
	v_rcp_f32_e32 v27, v27
	v_mul_f32_e32 v15, 0x3fb8aa3b, v15
	v_add_f32_e32 v28, 1.0, v28
	v_rcp_f32_e32 v28, v28
	v_mul_f32_e32 v27, 0xc1000000, v27
	v_mul_f32_e32 v27, v27, v43
	v_mul_f32_e32 v27, 0x3fb8aa3b, v27
	v_exp_f32_e32 v27, v27
	v_exp_f32_e32 v15, v15
	v_add_f32_e32 v11, 1.0, v11
	v_rcp_f32_e32 v11, v11
	v_fma_f32 v29, -v27, v27, 1.0
	v_max_f32_e32 v29, 0, v29
	v_cmp_gt_f32_e32 vcc, s5, v29
	v_mul_f32_e32 v30, 0x4f800000, v29
	ds_write_b32 v0, v27 offset:18440
	v_cndmask_b32_e32 v29, v29, v30, vcc
	v_sqrt_f32_e32 v30, v29
	v_add_f32_e32 v12, v12, v42
	v_mul_f32_e32 v12, 0xbfb8aa3b, v12
	v_exp_f32_e32 v12, v12
	v_add_u32_e32 v31, -1, v30
	v_fma_f32 v32, -v31, v30, v29
	v_cmp_ge_f32_e64 s[10:11], 0, v32
	v_add_u32_e32 v32, 1, v30
	v_add_f32_e32 v12, 1.0, v12
	v_cndmask_b32_e64 v31, v30, v31, s[10:11]
	v_fma_f32 v30, -v32, v30, v29
	v_cmp_lt_f32_e64 s[10:11], 0, v30
	v_rcp_f32_e32 v12, v12
	v_add_f32_e32 v6, v6, v37
	v_cndmask_b32_e64 v30, v31, v32, s[10:11]
	v_mul_f32_e32 v31, 0x37800000, v30
	v_cndmask_b32_e32 v30, v30, v31, vcc
	v_cmp_class_f32_e32 vcc, v29, v196
	v_mul_f32_e32 v6, 0xbfb8aa3b, v6
	v_exp_f32_e32 v6, v6
	v_cndmask_b32_e32 v29, v30, v29, vcc
	ds_read_u16 v30, v26 offset:544
	v_mul_f32_e32 v27, v28, v29
	v_add_f32_e32 v6, 1.0, v6
	v_rcp_f32_e32 v6, v6
	v_add_f32_e32 v2, v2, v42
	s_waitcnt lgkmcnt(0)
	v_lshlrev_b32_e32 v30, 16, v30
	v_mul_f32_e32 v27, v27, v30
	ds_write_b32 v0, v27 offset:51464
	v_rcp_f32_e32 v27, v18
	v_mul_f32_e32 v18, 0xc1000000, v22
	v_mul_f32_e32 v18, v18, v43
	v_mul_f32_e32 v18, 0x3fb8aa3b, v18
	v_exp_f32_e32 v22, v18
	v_mul_f32_e32 v6, 0xc1000000, v6
	v_mul_f32_e32 v6, v6, v43
	v_mul_f32_e32 v6, 0x3fb8aa3b, v6
	v_fma_f32 v18, -v22, v22, 1.0
	v_max_f32_e32 v18, 0, v18
	v_cmp_gt_f32_e32 vcc, s5, v18
	v_mul_f32_e32 v28, 0x4f800000, v18
	v_exp_f32_e32 v6, v6
	v_cndmask_b32_e32 v18, v18, v28, vcc
	v_sqrt_f32_e32 v28, v18
	v_mul_f32_e32 v2, 0xbfb8aa3b, v2
	v_exp_f32_e32 v2, v2
	v_add_f32_e32 v3, v3, v42
	v_add_u32_e32 v29, -1, v28
	v_fma_f32 v30, -v29, v28, v18
	v_cmp_ge_f32_e64 s[10:11], 0, v30
	v_add_u32_e32 v30, 1, v28
	v_add_f32_e32 v2, 1.0, v2
	v_cndmask_b32_e64 v29, v28, v29, s[10:11]
	v_fma_f32 v28, -v30, v28, v18
	v_cmp_lt_f32_e64 s[10:11], 0, v28
	v_rcp_f32_e32 v2, v2
	v_mul_f32_e32 v3, 0xbfb8aa3b, v3
	v_cndmask_b32_e64 v28, v29, v30, s[10:11]
	v_mul_f32_e32 v29, 0x37800000, v28
	v_cndmask_b32_e32 v28, v28, v29, vcc
	v_cmp_class_f32_e32 vcc, v18, v196
	v_exp_f32_e32 v3, v3
	v_add_f32_e32 v4, v4, v42
	v_cndmask_b32_e32 v28, v28, v18, vcc
	ds_read_u16 v18, v26 offset:4080
	v_mul_f32_e32 v27, v27, v28
	v_fma_f32 v28, -v23, v23, 1.0
	v_max_f32_e32 v28, 0, v28
	v_cmp_gt_f32_e32 vcc, s5, v28
	s_waitcnt lgkmcnt(0)
	v_lshlrev_b32_e32 v29, 16, v18
	v_mul_f32_e32 v27, v27, v29
	v_mul_f32_e32 v29, 0x4f800000, v28
	v_cndmask_b32_e32 v28, v28, v29, vcc
	v_sqrt_f32_e32 v29, v28
	v_add_u32_e32 v18, 0x1e3c, v0
	v_add_f32_e32 v3, 1.0, v3
	v_rcp_f32_e32 v3, v3
	v_add_u32_e32 v30, -1, v29
	v_fma_f32 v31, -v30, v29, v28
	v_cmp_ge_f32_e64 s[10:11], 0, v31
	v_add_u32_e32 v31, 1, v29
	v_mul_f32_e32 v4, 0xbfb8aa3b, v4
	v_cndmask_b32_e64 v30, v29, v30, s[10:11]
	v_fma_f32 v29, -v31, v29, v28
	v_cmp_lt_f32_e64 s[10:11], 0, v29
	v_exp_f32_e32 v4, v4
	s_movk_i32 s4, 0x80
	v_cndmask_b32_e64 v29, v30, v31, s[10:11]
	v_mul_f32_e32 v30, 0x37800000, v29
	v_cndmask_b32_e32 v29, v29, v30, vcc
	v_cmp_class_f32_e32 vcc, v28, v196
	v_add_u32_e32 v30, 0x6200, v0
	ds_write2_b32 v30, v22, v23 offset0:15 offset1:144
	v_cndmask_b32_e32 v28, v29, v28, vcc
	ds_read_u16 v29, v26 offset:4352
	v_mul_f32_e32 v19, v19, v28
	v_add_u32_e32 v22, 0xe200, v0
	v_add_f32_e32 v4, 1.0, v4
	v_rcp_f32_e32 v4, v4
	s_waitcnt lgkmcnt(0)
	v_lshlrev_b32_e32 v29, 16, v29
	v_mul_f32_e32 v19, v19, v29
	ds_write2_b32 v22, v27, v19 offset0:79 offset1:208
	v_add_f32_e32 v19, v24, v37
	v_mul_f32_e32 v19, 0xbfb8aa3b, v19
	v_exp_f32_e32 v19, v19
	s_nop 0
	v_add_f32_e32 v19, 1.0, v19
	v_rcp_f32_e32 v19, v19
	s_nop 0
	v_mul_f32_e32 v19, 0xc1000000, v19
	v_mul_f32_e32 v19, v19, v43
	v_mul_f32_e32 v19, 0x3fb8aa3b, v19
	v_exp_f32_e32 v19, v19
	s_nop 0
	v_fma_f32 v22, -v19, v19, 1.0
	v_max_f32_e32 v22, 0, v22
	v_cmp_gt_f32_e32 vcc, s5, v22
	v_mul_f32_e32 v23, 0x4f800000, v22
	s_nop 0
	v_cndmask_b32_e32 v22, v22, v23, vcc
	v_sqrt_f32_e32 v23, v22
	s_nop 0
	v_add_u32_e32 v24, -1, v23
	v_fma_f32 v27, -v24, v23, v22
	v_cmp_ge_f32_e64 s[10:11], 0, v27
	v_add_u32_e32 v27, 1, v23
	s_nop 0
	v_cndmask_b32_e64 v24, v23, v24, s[10:11]
	v_fma_f32 v23, -v27, v23, v22
	v_cmp_lt_f32_e64 s[10:11], 0, v23
	s_nop 1
	v_cndmask_b32_e64 v23, v24, v27, s[10:11]
	v_mul_f32_e32 v24, 0x37800000, v23
	v_cndmask_b32_e32 v23, v23, v24, vcc
	v_cmp_class_f32_e32 vcc, v22, v196
	s_nop 1
	v_cndmask_b32_e32 v22, v23, v22, vcc
	v_mul_f32_e32 v20, v20, v22
	v_add_f32_e32 v22, v25, v37
	v_mul_f32_e32 v22, 0xbfb8aa3b, v22
	v_exp_f32_e32 v22, v22
	ds_read_u16 v23, v26 offset:4624
	v_add_f32_e32 v22, 1.0, v22
	v_rcp_f32_e32 v22, v22
	s_waitcnt lgkmcnt(0)
	v_lshlrev_b32_e32 v23, 16, v23
	v_mul_f32_e32 v20, v20, v23
	v_mul_f32_e32 v22, 0xc1000000, v22
	v_mul_f32_e32 v22, v22, v43
	v_mul_f32_e32 v22, 0x3fb8aa3b, v22
	v_exp_f32_e32 v22, v22
	s_nop 0
	v_fma_f32 v23, -v22, v22, 1.0
	v_max_f32_e32 v23, 0, v23
	v_cmp_gt_f32_e32 vcc, s5, v23
	v_mul_f32_e32 v24, 0x4f800000, v23
	s_nop 0
	v_cndmask_b32_e32 v23, v23, v24, vcc
	v_sqrt_f32_e32 v24, v23
	s_nop 0
	v_add_u32_e32 v25, -1, v24
	v_fma_f32 v27, -v25, v24, v23
	v_cmp_ge_f32_e64 s[10:11], 0, v27
	v_add_u32_e32 v27, 1, v24
	s_nop 0
	v_cndmask_b32_e64 v25, v24, v25, s[10:11]
	v_fma_f32 v24, -v27, v24, v23
	v_cmp_lt_f32_e64 s[10:11], 0, v24
	s_nop 1
	v_cndmask_b32_e64 v24, v25, v27, s[10:11]
	v_mul_f32_e32 v25, 0x37800000, v24
	v_cndmask_b32_e32 v24, v24, v25, vcc
	v_cmp_class_f32_e32 vcc, v23, v196
	v_add_u32_e32 v25, 0x6600, v0
	ds_write2_b32 v25, v19, v22 offset0:17 offset1:146
	v_cndmask_b32_e32 v23, v24, v23, vcc
	ds_read_u16 v24, v26 offset:4896
	v_mul_f32_e32 v19, v21, v23
	v_add_u32_e32 v21, 0xe600, v0
	s_waitcnt lgkmcnt(0)
	v_lshlrev_b32_e32 v24, 16, v24
	v_mul_f32_e32 v19, v19, v24
	ds_write2_b32 v21, v20, v19 offset0:81 offset1:210
	v_rcp_f32_e32 v19, v10
	v_mul_f32_e32 v10, 0xc1000000, v14
	v_mul_f32_e32 v10, v10, v43
	v_mul_f32_e32 v10, 0x3fb8aa3b, v10
	v_exp_f32_e32 v14, v10
	s_nop 0
	v_fma_f32 v10, -v14, v14, 1.0
	v_max_f32_e32 v10, 0, v10
	v_cmp_gt_f32_e32 vcc, s5, v10
	v_mul_f32_e32 v20, 0x4f800000, v10
	s_nop 0
	v_cndmask_b32_e32 v10, v10, v20, vcc
	v_sqrt_f32_e32 v20, v10
	s_nop 0
	v_add_u32_e32 v21, -1, v20
	v_fma_f32 v22, -v21, v20, v10
	v_cmp_ge_f32_e64 s[10:11], 0, v22
	v_add_u32_e32 v22, 1, v20
	s_nop 0
	v_cndmask_b32_e64 v21, v20, v21, s[10:11]
	v_fma_f32 v20, -v22, v20, v10
	v_cmp_lt_f32_e64 s[10:11], 0, v20
	s_nop 1
	v_cndmask_b32_e64 v20, v21, v22, s[10:11]
	v_mul_f32_e32 v21, 0x37800000, v20
	v_cndmask_b32_e32 v20, v20, v21, vcc
	v_cmp_class_f32_e32 vcc, v10, v196
	s_nop 1
	v_cndmask_b32_e32 v20, v20, v10, vcc
	ds_read_u16 v10, v26 offset:8432
	v_mul_f32_e32 v19, v19, v20
	v_add_u32_e32 v20, 0x1037c, v0
	s_waitcnt lgkmcnt(0)
	v_lshlrev_b32_e32 v21, 16, v10
	v_mul_f32_e32 v19, v19, v21
	ds_write_b32 v20, v19
	v_fma_f32 v19, -v15, v15, 1.0
	v_max_f32_e32 v19, 0, v19
	v_cmp_gt_f32_e32 vcc, s5, v19
	v_mul_f32_e32 v20, 0x4f800000, v19
	v_add_u32_e32 v10, 0x3e7c, v0
	v_cndmask_b32_e32 v19, v19, v20, vcc
	v_sqrt_f32_e32 v20, v19
	s_nop 0
	v_add_u32_e32 v21, -1, v20
	v_fma_f32 v22, -v21, v20, v19
	v_cmp_ge_f32_e64 s[10:11], 0, v22
	v_add_u32_e32 v22, 1, v20
	s_nop 0
	v_cndmask_b32_e64 v21, v20, v21, s[10:11]
	v_fma_f32 v20, -v22, v20, v19
	v_cmp_lt_f32_e64 s[10:11], 0, v20
	s_nop 1
	v_cndmask_b32_e64 v20, v21, v22, s[10:11]
	v_mul_f32_e32 v21, 0x37800000, v20
	v_cndmask_b32_e32 v20, v20, v21, vcc
	v_add_u32_e32 v21, 0x8200, v0
	ds_write2_b32 v21, v14, v15 offset0:31 offset1:160
	v_add_f32_e32 v14, v16, v37
	v_mul_f32_e32 v14, 0xbfb8aa3b, v14
	v_exp_f32_e32 v14, v14
	v_cmp_class_f32_e32 vcc, v19, v196
	v_add_f32_e32 v14, 1.0, v14
	v_rcp_f32_e32 v14, v14
	v_cndmask_b32_e32 v19, v20, v19, vcc
	ds_read_u16 v20, v26 offset:8704
	v_mul_f32_e32 v11, v11, v19
	v_mul_f32_e32 v14, 0xc1000000, v14
	v_mul_f32_e32 v14, v14, v43
	v_mul_f32_e32 v14, 0x3fb8aa3b, v14
	v_exp_f32_e32 v14, v14
	s_waitcnt lgkmcnt(0)
	v_lshlrev_b32_e32 v20, 16, v20
	v_mul_f32_e32 v11, v11, v20
	v_fma_f32 v15, -v14, v14, 1.0
	v_max_f32_e32 v15, 0, v15
	v_cmp_gt_f32_e32 vcc, s5, v15
	v_mul_f32_e32 v16, 0x4f800000, v15
	s_nop 0
	v_cndmask_b32_e32 v15, v15, v16, vcc
	v_sqrt_f32_e32 v16, v15
	s_nop 0
	v_add_u32_e32 v19, -1, v16
	v_fma_f32 v20, -v19, v16, v15
	v_cmp_ge_f32_e64 s[10:11], 0, v20
	v_add_u32_e32 v20, 1, v16
	s_nop 0
	v_cndmask_b32_e64 v19, v16, v19, s[10:11]
	v_fma_f32 v16, -v20, v16, v15
	v_cmp_lt_f32_e64 s[10:11], 0, v16
	s_nop 1
	v_cndmask_b32_e64 v16, v19, v20, s[10:11]
	v_mul_f32_e32 v19, 0x37800000, v16
	v_cndmask_b32_e32 v16, v16, v19, vcc
	v_cmp_class_f32_e32 vcc, v15, v196
	s_nop 1
	v_cndmask_b32_e32 v15, v16, v15, vcc
	ds_read_u16 v16, v26 offset:8976
	v_mul_f32_e32 v12, v12, v15
	v_add_u32_e32 v15, 0xe600, v18
	s_waitcnt lgkmcnt(0)
	v_lshlrev_b32_e32 v16, 16, v16
	v_mul_f32_e32 v12, v12, v16
	ds_write2_b32 v15, v11, v12 offset0:81 offset1:210
	v_add_f32_e32 v11, v17, v37
	v_mul_f32_e32 v11, 0xbfb8aa3b, v11
	v_exp_f32_e32 v11, v11
	v_add_f32_e32 v12, v13, v42
	v_mul_f32_e32 v12, 0xbfb8aa3b, v12
	v_exp_f32_e32 v12, v12
	v_add_f32_e32 v11, 1.0, v11
	v_rcp_f32_e32 v11, v11
	v_add_f32_e32 v12, 1.0, v12
	v_rcp_f32_e32 v12, v12
	v_mul_f32_e32 v11, 0xc1000000, v11
	v_mul_f32_e32 v11, v11, v43
	v_mul_f32_e32 v11, 0x3fb8aa3b, v11
	v_exp_f32_e32 v11, v11
	s_nop 0
	v_fma_f32 v13, -v11, v11, 1.0
	v_max_f32_e32 v13, 0, v13
	v_cmp_gt_f32_e32 vcc, s5, v13
	v_mul_f32_e32 v15, 0x4f800000, v13
	s_nop 0
	v_cndmask_b32_e32 v13, v13, v15, vcc
	v_sqrt_f32_e32 v15, v13
	s_nop 0
	v_add_u32_e32 v16, -1, v15
	v_fma_f32 v17, -v16, v15, v13
	v_cmp_ge_f32_e64 s[10:11], 0, v17
	v_add_u32_e32 v17, 1, v15
	s_nop 0
	v_cndmask_b32_e64 v16, v15, v16, s[10:11]
	v_fma_f32 v15, -v17, v15, v13
	v_cmp_lt_f32_e64 s[10:11], 0, v15
	s_nop 1
	v_cndmask_b32_e64 v15, v16, v17, s[10:11]
	v_mul_f32_e32 v16, 0x37800000, v15
	v_cndmask_b32_e32 v15, v15, v16, vcc
	v_cmp_class_f32_e32 vcc, v13, v196
	v_add_u32_e32 v16, 0x8600, v0
	ds_write2_b32 v16, v14, v11 offset0:33 offset1:162
	v_cndmask_b32_e32 v13, v15, v13, vcc
	ds_read_u16 v15, v26 offset:9248
	v_mul_f32_e32 v11, v12, v13
	s_waitcnt lgkmcnt(0)
	v_lshlrev_b32_e32 v15, 16, v15
	v_mul_f32_e32 v11, v11, v15
	ds_write_b32 v18, v11 offset:60236
	v_fma_f32 v11, -v6, v6, 1.0
	v_max_f32_e32 v11, 0, v11
	v_cmp_gt_f32_e32 vcc, s5, v11
	v_mul_f32_e32 v12, 0x4f800000, v11
	s_nop 0
	v_cndmask_b32_e32 v11, v11, v12, vcc
	v_sqrt_f32_e32 v12, v11
	s_nop 0
	v_add_u32_e32 v13, -1, v12
	v_fma_f32 v14, -v13, v12, v11
	v_cmp_ge_f32_e64 s[10:11], 0, v14
	v_add_u32_e32 v14, 1, v12
	s_nop 0
	v_cndmask_b32_e64 v13, v12, v13, s[10:11]
	v_fma_f32 v12, -v14, v12, v11
	v_cmp_lt_f32_e64 s[10:11], 0, v12
	s_nop 1
	v_cndmask_b32_e64 v12, v13, v14, s[10:11]
	v_mul_f32_e32 v13, 0x37800000, v12
	v_cndmask_b32_e32 v12, v12, v13, vcc
	v_cmp_class_f32_e32 vcc, v11, v196
	s_nop 1
	v_cndmask_b32_e32 v11, v12, v11, vcc
	ds_read_u16 v12, v26 offset:12784
	v_mul_f32_e32 v2, v2, v11
	v_add_u32_e32 v11, 0x123bc, v0
	s_waitcnt lgkmcnt(0)
	v_lshlrev_b32_e32 v12, 16, v12
	v_mul_f32_e32 v2, v2, v12
	ds_write_b32 v11, v2
	v_add_f32_e32 v2, v7, v37
	v_mul_f32_e32 v2, 0xbfb8aa3b, v2
	v_exp_f32_e32 v2, v2
	s_nop 0
	v_add_f32_e32 v2, 1.0, v2
	v_rcp_f32_e32 v2, v2
	s_nop 0
	v_mul_f32_e32 v2, 0xc1000000, v2
	v_mul_f32_e32 v2, v2, v43
	v_mul_f32_e32 v2, 0x3fb8aa3b, v2
	v_exp_f32_e32 v2, v2
	s_nop 0
	v_fma_f32 v7, -v2, v2, 1.0
	v_max_f32_e32 v7, 0, v7
	v_cmp_gt_f32_e32 vcc, s5, v7
	v_mul_f32_e32 v11, 0x4f800000, v7
	s_nop 0
	v_cndmask_b32_e32 v7, v7, v11, vcc
	v_sqrt_f32_e32 v11, v7
	s_nop 0
	v_add_u32_e32 v12, -1, v11
	v_fma_f32 v13, -v12, v11, v7
	v_cmp_ge_f32_e64 s[10:11], 0, v13
	v_add_u32_e32 v13, 1, v11
	s_nop 0
	v_cndmask_b32_e64 v12, v11, v12, s[10:11]
	v_fma_f32 v11, -v13, v11, v7
	v_cmp_lt_f32_e64 s[10:11], 0, v11
	s_nop 1
	v_cndmask_b32_e64 v11, v12, v13, s[10:11]
	v_mul_f32_e32 v12, 0x37800000, v11
	v_cndmask_b32_e32 v11, v11, v12, vcc
	v_cmp_class_f32_e32 vcc, v7, v196
	v_add_u32_e32 v12, 0xa200, v0
	ds_write2_b32 v12, v6, v2 offset0:47 offset1:176
	v_cndmask_b32_e32 v7, v11, v7, vcc
	ds_read_u16 v11, v26 offset:13056
	v_mul_f32_e32 v2, v3, v7
	v_add_u32_e32 v0, 0xa600, v0
	s_waitcnt lgkmcnt(0)
	v_lshlrev_b32_e32 v11, 16, v11
	v_mul_f32_e32 v3, v2, v11
	v_add_f32_e32 v2, v8, v37
	v_mul_f32_e32 v2, 0xbfb8aa3b, v2
	v_exp_f32_e32 v2, v2
	s_nop 0
	v_add_f32_e32 v2, 1.0, v2
	v_rcp_f32_e32 v2, v2
	s_nop 0
	v_mul_f32_e32 v2, 0xc1000000, v2
	v_mul_f32_e32 v2, v2, v43
	v_mul_f32_e32 v2, 0x3fb8aa3b, v2
	v_exp_f32_e32 v2, v2
	s_nop 0
	v_fma_f32 v6, -v2, v2, 1.0
	v_max_f32_e32 v6, 0, v6
	v_cmp_gt_f32_e32 vcc, s5, v6
	v_mul_f32_e32 v7, 0x4f800000, v6
	s_nop 0
	v_cndmask_b32_e32 v6, v6, v7, vcc
	v_sqrt_f32_e32 v7, v6
	s_nop 0
	v_add_u32_e32 v8, -1, v7
	v_fma_f32 v11, -v8, v7, v6
	v_cmp_ge_f32_e64 s[10:11], 0, v11
	v_add_u32_e32 v11, 1, v7
	s_nop 0
	v_cndmask_b32_e64 v8, v7, v8, s[10:11]
	v_fma_f32 v7, -v11, v7, v6
	v_cmp_lt_f32_e64 s[10:11], 0, v7
	s_nop 1
	v_cndmask_b32_e64 v7, v8, v11, s[10:11]
	v_mul_f32_e32 v8, 0x37800000, v7
	v_cndmask_b32_e32 v7, v7, v8, vcc
	v_cmp_class_f32_e32 vcc, v6, v196
	s_nop 1
	v_cndmask_b32_e32 v6, v7, v6, vcc
	ds_read_u16 v7, v26 offset:13328
	v_mul_f32_e32 v4, v4, v6
	v_add_u32_e32 v6, 0xe600, v10
	s_waitcnt lgkmcnt(0)
	v_lshlrev_b32_e32 v7, 16, v7
	v_mul_f32_e32 v4, v4, v7
	ds_write2_b32 v6, v3, v4 offset0:81 offset1:210
	v_add_f32_e32 v3, v9, v37
	v_mul_f32_e32 v3, 0xbfb8aa3b, v3
	v_exp_f32_e32 v3, v3
	s_nop 0
	v_add_f32_e32 v3, 1.0, v3
	v_rcp_f32_e32 v4, v3
	v_add_f32_e32 v3, v5, v42
	v_mul_f32_e32 v3, 0xbfb8aa3b, v3
	v_exp_f32_e32 v3, v3
	v_mul_f32_e32 v4, 0xc1000000, v4
	v_mul_f32_e32 v4, v4, v43
	v_mul_f32_e32 v4, 0x3fb8aa3b, v4
	v_exp_f32_e32 v4, v4
	v_add_f32_e32 v3, 1.0, v3
	v_rcp_f32_e32 v3, v3
	v_fma_f32 v5, -v4, v4, 1.0
	v_max_f32_e32 v5, 0, v5
	v_cmp_gt_f32_e32 vcc, s5, v5
	v_mul_f32_e32 v6, 0x4f800000, v5
	ds_write2_b32 v0, v2, v4 offset0:49 offset1:178
	v_cndmask_b32_e32 v5, v5, v6, vcc
	v_sqrt_f32_e32 v6, v5
	s_nop 0
	v_add_u32_e32 v7, -1, v6
	v_fma_f32 v8, -v7, v6, v5
	v_cmp_ge_f32_e64 s[10:11], 0, v8
	v_add_u32_e32 v8, 1, v6
	s_nop 0
	v_cndmask_b32_e64 v7, v6, v7, s[10:11]
	v_fma_f32 v6, -v8, v6, v5
	v_cmp_lt_f32_e64 s[10:11], 0, v6
	s_nop 1
	v_cndmask_b32_e64 v6, v7, v8, s[10:11]
	v_mul_f32_e32 v7, 0x37800000, v6
	v_cndmask_b32_e32 v6, v6, v7, vcc
	v_cmp_class_f32_e32 vcc, v5, v196
	s_nop 1
	v_cndmask_b32_e32 v5, v6, v5, vcc
	ds_read_u16 v6, v26 offset:13600
	v_mul_f32_e32 v0, v3, v5
	v_cmp_gt_i32_e32 vcc, s4, v39
	s_waitcnt lgkmcnt(0)
	v_lshlrev_b32_e32 v6, 16, v6
	v_mul_f32_e32 v0, v0, v6
	ds_write_b32 v10, v0 offset:60236
	s_waitcnt lgkmcnt(0)
	s_barrier
	s_and_saveexec_b64 s[10:11], vcc
	s_cbranch_execz .LBB0_654
	v_readlane_b32 s4, v250, 40
	v_lshl_add_u32 v0, v39, 1, 0
	v_mov_b32_e32 v3, 0
	v_lshl_add_u32 v4, v39, 2, s4
	v_mov_b32_e32 v2, 1.0
	s_movk_i32 s4, 0xbc00
	v_add_u32_e32 v8, 0x14600, v0
	v_add_u32_e32 v5, 0x0, v4
	ds_read2_b32 v[70:71], v5 offset1:129
	v_add_u32_e32 v6, 0x8100, v4
	ds_read2_b32 v[102:103], v6 offset1:129
	v_add_u32_e32 v5, 0x408, v4
	ds_read2_b32 v[72:73], v5 offset1:129
	v_add_u32_e32 v6, 0x8508, v4
	ds_read2_b32 v[104:105], v6 offset1:129
	v_add_u32_e32 v5, 0x810, v4
	ds_read2_b32 v[74:75], v5 offset1:129
	v_add_u32_e32 v6, 0x8910, v4
	ds_read2_b32 v[106:107], v6 offset1:129
	v_add_u32_e32 v5, 0xc18, v4
	ds_read2_b32 v[76:77], v5 offset1:129
	v_add_u32_e32 v6, 0x8d18, v4
	ds_read2_b32 v[108:109], v6 offset1:129
	v_add_u32_e32 v5, 0x1020, v4
	ds_read2_b32 v[78:79], v5 offset1:129
	v_add_u32_e32 v6, 0x9120, v4
	ds_read2_b32 v[110:111], v6 offset1:129
	v_add_u32_e32 v5, 0x1428, v4
	ds_read2_b32 v[80:81], v5 offset1:129
	v_add_u32_e32 v6, 0x9528, v4
	ds_read2_b32 v[112:113], v6 offset1:129
	v_add_u32_e32 v5, 0x1830, v4
	ds_read2_b32 v[82:83], v5 offset1:129
	v_add_u32_e32 v6, 0x9930, v4
	ds_read2_b32 v[114:115], v6 offset1:129
	v_add_u32_e32 v5, 0x1c38, v4
	ds_read2_b32 v[84:85], v5 offset1:129
	v_add_u32_e32 v6, 0x9d38, v4
	ds_read2_b32 v[116:117], v6 offset1:129
	v_add_u32_e32 v5, 0x2040, v4
	ds_read2_b32 v[86:87], v5 offset1:129
	v_add_u32_e32 v6, 0xa140, v4
	ds_read2_b32 v[118:119], v6 offset1:129
	v_add_u32_e32 v5, 0x2448, v4
	ds_read2_b32 v[88:89], v5 offset1:129
	v_add_u32_e32 v6, 0xa548, v4
	ds_read2_b32 v[120:121], v6 offset1:129
	v_add_u32_e32 v5, 0x2850, v4
	ds_read2_b32 v[90:91], v5 offset1:129
	v_add_u32_e32 v6, 0xa950, v4
	ds_read2_b32 v[122:123], v6 offset1:129
	v_add_u32_e32 v5, 0x2c58, v4
	ds_read2_b32 v[92:93], v5 offset1:129
	v_add_u32_e32 v6, 0xad58, v4
	ds_read2_b32 v[124:125], v6 offset1:129
	v_add_u32_e32 v5, 0x3060, v4
	ds_read2_b32 v[94:95], v5 offset1:129
	v_add_u32_e32 v6, 0xb160, v4
	ds_read2_b32 v[126:127], v6 offset1:129
	v_add_u32_e32 v5, 0x3468, v4
	ds_read2_b32 v[96:97], v5 offset1:129
	v_add_u32_e32 v6, 0xb568, v4
	ds_read2_b32 v[128:129], v6 offset1:129
	v_add_u32_e32 v5, 0x3870, v4
	ds_read2_b32 v[98:99], v5 offset1:129
	v_add_u32_e32 v6, 0xb970, v4
	ds_read2_b32 v[130:131], v6 offset1:129
	v_add_u32_e32 v5, 0x3c78, v4
	ds_read2_b32 v[100:101], v5 offset1:129
	v_add_u32_e32 v6, 0xbd78, v4
	ds_read2_b32 v[132:133], v6 offset1:129
	s_waitcnt lgkmcnt(0)
	v_mul_f32_e32 v2, v2, v70
	v_fma_f32 v3, v3, v70, v102
	v_cvt_pk_bf16_f32 v9, v3, s0
	ds_write_b16 v0, v9
	v_cvt_pk_bf16_f32 v10, v2, s0
	ds_write_b16 v8, v10
	v_mul_f32_e32 v2, v2, v71
	v_fma_f32 v3, v3, v71, v103
	v_cvt_pk_bf16_f32 v11, v3, s0
	ds_write_b16 v0, v11 offset:272
	v_cvt_pk_bf16_f32 v12, v2, s0
	ds_write_b16 v8, v12 offset:272
	v_mul_f32_e32 v2, v2, v72
	v_fma_f32 v3, v3, v72, v104
	v_cvt_pk_bf16_f32 v9, v3, s0
	ds_write_b16 v0, v9 offset:544
	v_cvt_pk_bf16_f32 v10, v2, s0
	ds_write_b16 v8, v10 offset:544
	v_mul_f32_e32 v2, v2, v73
	v_fma_f32 v3, v3, v73, v105
	v_cvt_pk_bf16_f32 v11, v3, s0
	ds_write_b16 v0, v11 offset:816
	v_cvt_pk_bf16_f32 v12, v2, s0
	ds_write_b16 v8, v12 offset:816
	v_mul_f32_e32 v2, v2, v74
	v_fma_f32 v3, v3, v74, v106
	v_cvt_pk_bf16_f32 v9, v3, s0
	ds_write_b16 v0, v9 offset:1088
	v_cvt_pk_bf16_f32 v10, v2, s0
	ds_write_b16 v8, v10 offset:1088
	v_mul_f32_e32 v2, v2, v75
	v_fma_f32 v3, v3, v75, v107
	v_cvt_pk_bf16_f32 v11, v3, s0
	ds_write_b16 v0, v11 offset:1360
	v_cvt_pk_bf16_f32 v12, v2, s0
	ds_write_b16 v8, v12 offset:1360
	v_mul_f32_e32 v2, v2, v76
	v_fma_f32 v3, v3, v76, v108
	v_cvt_pk_bf16_f32 v9, v3, s0
	ds_write_b16 v0, v9 offset:1632
	v_cvt_pk_bf16_f32 v10, v2, s0
	ds_write_b16 v8, v10 offset:1632
	v_mul_f32_e32 v2, v2, v77
	v_fma_f32 v3, v3, v77, v109
	v_cvt_pk_bf16_f32 v11, v3, s0
	ds_write_b16 v0, v11 offset:1904
	v_cvt_pk_bf16_f32 v12, v2, s0
	ds_write_b16 v8, v12 offset:1904
	v_mul_f32_e32 v2, v2, v78
	v_fma_f32 v3, v3, v78, v110
	v_cvt_pk_bf16_f32 v9, v3, s0
	ds_write_b16 v0, v9 offset:2176
	v_cvt_pk_bf16_f32 v10, v2, s0
	ds_write_b16 v8, v10 offset:2176
	v_mul_f32_e32 v2, v2, v79
	v_fma_f32 v3, v3, v79, v111
	v_cvt_pk_bf16_f32 v11, v3, s0
	ds_write_b16 v0, v11 offset:2448
	v_cvt_pk_bf16_f32 v12, v2, s0
	ds_write_b16 v8, v12 offset:2448
	v_mul_f32_e32 v2, v2, v80
	v_fma_f32 v3, v3, v80, v112
	v_cvt_pk_bf16_f32 v9, v3, s0
	ds_write_b16 v0, v9 offset:2720
	v_cvt_pk_bf16_f32 v10, v2, s0
	ds_write_b16 v8, v10 offset:2720
	v_mul_f32_e32 v2, v2, v81
	v_fma_f32 v3, v3, v81, v113
	v_cvt_pk_bf16_f32 v11, v3, s0
	ds_write_b16 v0, v11 offset:2992
	v_cvt_pk_bf16_f32 v12, v2, s0
	ds_write_b16 v8, v12 offset:2992
	v_mul_f32_e32 v2, v2, v82
	v_fma_f32 v3, v3, v82, v114
	v_cvt_pk_bf16_f32 v9, v3, s0
	ds_write_b16 v0, v9 offset:3264
	v_cvt_pk_bf16_f32 v10, v2, s0
	ds_write_b16 v8, v10 offset:3264
	v_mul_f32_e32 v2, v2, v83
	v_fma_f32 v3, v3, v83, v115
	v_cvt_pk_bf16_f32 v11, v3, s0
	ds_write_b16 v0, v11 offset:3536
	v_cvt_pk_bf16_f32 v12, v2, s0
	ds_write_b16 v8, v12 offset:3536
	v_mul_f32_e32 v2, v2, v84
	v_fma_f32 v3, v3, v84, v116
	v_cvt_pk_bf16_f32 v9, v3, s0
	ds_write_b16 v0, v9 offset:3808
	v_cvt_pk_bf16_f32 v10, v2, s0
	ds_write_b16 v8, v10 offset:3808
	v_mul_f32_e32 v2, v2, v85
	v_fma_f32 v3, v3, v85, v117
	v_cvt_pk_bf16_f32 v11, v3, s0
	ds_write_b16 v0, v11 offset:4080
	v_cvt_pk_bf16_f32 v12, v2, s0
	ds_write_b16 v8, v12 offset:4080
	v_mul_f32_e32 v2, v2, v86
	v_fma_f32 v3, v3, v86, v118
	v_cvt_pk_bf16_f32 v9, v3, s0
	ds_write_b16 v0, v9 offset:4352
	v_cvt_pk_bf16_f32 v10, v2, s0
	ds_write_b16 v8, v10 offset:4352
	v_mul_f32_e32 v2, v2, v87
	v_fma_f32 v3, v3, v87, v119
	v_cvt_pk_bf16_f32 v11, v3, s0
	ds_write_b16 v0, v11 offset:4624
	v_cvt_pk_bf16_f32 v12, v2, s0
	ds_write_b16 v8, v12 offset:4624
	v_mul_f32_e32 v2, v2, v88
	v_fma_f32 v3, v3, v88, v120
	v_cvt_pk_bf16_f32 v9, v3, s0
	ds_write_b16 v0, v9 offset:4896
	v_cvt_pk_bf16_f32 v10, v2, s0
	ds_write_b16 v8, v10 offset:4896
	v_mul_f32_e32 v2, v2, v89
	v_fma_f32 v3, v3, v89, v121
	v_cvt_pk_bf16_f32 v11, v3, s0
	ds_write_b16 v0, v11 offset:5168
	v_cvt_pk_bf16_f32 v12, v2, s0
	ds_write_b16 v8, v12 offset:5168
	v_mul_f32_e32 v2, v2, v90
	v_fma_f32 v3, v3, v90, v122
	v_cvt_pk_bf16_f32 v9, v3, s0
	ds_write_b16 v0, v9 offset:5440
	v_cvt_pk_bf16_f32 v10, v2, s0
	ds_write_b16 v8, v10 offset:5440
	v_mul_f32_e32 v2, v2, v91
	v_fma_f32 v3, v3, v91, v123
	v_cvt_pk_bf16_f32 v11, v3, s0
	ds_write_b16 v0, v11 offset:5712
	v_cvt_pk_bf16_f32 v12, v2, s0
	ds_write_b16 v8, v12 offset:5712
	v_mul_f32_e32 v2, v2, v92
	v_fma_f32 v3, v3, v92, v124
	v_cvt_pk_bf16_f32 v9, v3, s0
	ds_write_b16 v0, v9 offset:5984
	v_cvt_pk_bf16_f32 v10, v2, s0
	ds_write_b16 v8, v10 offset:5984
	v_mul_f32_e32 v2, v2, v93
	v_fma_f32 v3, v3, v93, v125
	v_cvt_pk_bf16_f32 v11, v3, s0
	ds_write_b16 v0, v11 offset:6256
	v_cvt_pk_bf16_f32 v12, v2, s0
	ds_write_b16 v8, v12 offset:6256
	v_mul_f32_e32 v2, v2, v94
	v_fma_f32 v3, v3, v94, v126
	v_cvt_pk_bf16_f32 v9, v3, s0
	ds_write_b16 v0, v9 offset:6528
	v_cvt_pk_bf16_f32 v10, v2, s0
	ds_write_b16 v8, v10 offset:6528
	v_mul_f32_e32 v2, v2, v95
	v_fma_f32 v3, v3, v95, v127
	v_cvt_pk_bf16_f32 v11, v3, s0
	ds_write_b16 v0, v11 offset:6800
	v_cvt_pk_bf16_f32 v12, v2, s0
	ds_write_b16 v8, v12 offset:6800
	v_mul_f32_e32 v2, v2, v96
	v_fma_f32 v3, v3, v96, v128
	v_cvt_pk_bf16_f32 v9, v3, s0
	ds_write_b16 v0, v9 offset:7072
	v_cvt_pk_bf16_f32 v10, v2, s0
	ds_write_b16 v8, v10 offset:7072
	v_mul_f32_e32 v2, v2, v97
	v_fma_f32 v3, v3, v97, v129
	v_cvt_pk_bf16_f32 v11, v3, s0
	ds_write_b16 v0, v11 offset:7344
	v_cvt_pk_bf16_f32 v12, v2, s0
	ds_write_b16 v8, v12 offset:7344
	v_mul_f32_e32 v2, v2, v98
	v_fma_f32 v3, v3, v98, v130
	v_cvt_pk_bf16_f32 v9, v3, s0
	ds_write_b16 v0, v9 offset:7616
	v_cvt_pk_bf16_f32 v10, v2, s0
	ds_write_b16 v8, v10 offset:7616
	v_mul_f32_e32 v2, v2, v99
	v_fma_f32 v3, v3, v99, v131
	v_cvt_pk_bf16_f32 v11, v3, s0
	ds_write_b16 v0, v11 offset:7888
	v_cvt_pk_bf16_f32 v12, v2, s0
	ds_write_b16 v8, v12 offset:7888
	v_mul_f32_e32 v2, v2, v100
	v_fma_f32 v3, v3, v100, v132
	v_cvt_pk_bf16_f32 v9, v3, s0
	ds_write_b16 v0, v9 offset:8160
	v_cvt_pk_bf16_f32 v10, v2, s0
	ds_write_b16 v8, v10 offset:8160
	v_mul_f32_e32 v2, v2, v101
	v_fma_f32 v3, v3, v101, v133
	v_cvt_pk_bf16_f32 v11, v3, s0
	ds_write_b16 v0, v11 offset:8432
	v_cvt_pk_bf16_f32 v12, v2, s0
	ds_write_b16 v8, v12 offset:8432
	v_add_u32_e32 v5, 0x4080, v4
	ds_read2_b32 v[70:71], v5 offset1:129
	v_add_u32_e32 v6, 0xc180, v4
	ds_read2_b32 v[102:103], v6 offset1:129
	v_add_u32_e32 v5, 0x4488, v4
	ds_read2_b32 v[72:73], v5 offset1:129
	v_add_u32_e32 v6, 0xc588, v4
	ds_read2_b32 v[104:105], v6 offset1:129
	v_add_u32_e32 v5, 0x4890, v4
	ds_read2_b32 v[74:75], v5 offset1:129
	v_add_u32_e32 v6, 0xc990, v4
	ds_read2_b32 v[106:107], v6 offset1:129
	v_add_u32_e32 v5, 0x4c98, v4
	ds_read2_b32 v[76:77], v5 offset1:129
	v_add_u32_e32 v6, 0xcd98, v4
	ds_read2_b32 v[108:109], v6 offset1:129
	v_add_u32_e32 v5, 0x50a0, v4
	ds_read2_b32 v[78:79], v5 offset1:129
	v_add_u32_e32 v6, 0xd1a0, v4
	ds_read2_b32 v[110:111], v6 offset1:129
	v_add_u32_e32 v5, 0x54a8, v4
	ds_read2_b32 v[80:81], v5 offset1:129
	v_add_u32_e32 v6, 0xd5a8, v4
	ds_read2_b32 v[112:113], v6 offset1:129
	v_add_u32_e32 v5, 0x58b0, v4
	ds_read2_b32 v[82:83], v5 offset1:129
	v_add_u32_e32 v6, 0xd9b0, v4
	ds_read2_b32 v[114:115], v6 offset1:129
	v_add_u32_e32 v5, 0x5cb8, v4
	ds_read2_b32 v[84:85], v5 offset1:129
	v_add_u32_e32 v6, 0xddb8, v4
	ds_read2_b32 v[116:117], v6 offset1:129
	v_add_u32_e32 v5, 0x60c0, v4
	ds_read2_b32 v[86:87], v5 offset1:129
	v_add_u32_e32 v6, 0xe1c0, v4
	ds_read2_b32 v[118:119], v6 offset1:129
	v_add_u32_e32 v5, 0x64c8, v4
	ds_read2_b32 v[88:89], v5 offset1:129
	v_add_u32_e32 v6, 0xe5c8, v4
	ds_read2_b32 v[120:121], v6 offset1:129
	v_add_u32_e32 v5, 0x68d0, v4
	ds_read2_b32 v[90:91], v5 offset1:129
	v_add_u32_e32 v6, 0xe9d0, v4
	ds_read2_b32 v[122:123], v6 offset1:129
	v_add_u32_e32 v5, 0x6cd8, v4
	ds_read2_b32 v[92:93], v5 offset1:129
	v_add_u32_e32 v6, 0xedd8, v4
	ds_read2_b32 v[124:125], v6 offset1:129
	v_add_u32_e32 v5, 0x70e0, v4
	ds_read2_b32 v[94:95], v5 offset1:129
	v_add_u32_e32 v6, 0xf1e0, v4
	ds_read2_b32 v[126:127], v6 offset1:129
	v_add_u32_e32 v5, 0x74e8, v4
	ds_read2_b32 v[96:97], v5 offset1:129
	v_add_u32_e32 v6, 0xf5e8, v4
	ds_read2_b32 v[128:129], v6 offset1:129
	v_add_u32_e32 v5, 0x78f0, v4
	ds_read2_b32 v[98:99], v5 offset1:129
	v_add_u32_e32 v6, 0xf9f0, v4
	ds_read2_b32 v[130:131], v6 offset1:129
	v_add_u32_e32 v5, 0x7cf8, v4
	ds_read2_b32 v[100:101], v5 offset1:129
	v_add_u32_e32 v6, 0xfdf8, v4
	ds_read2_b32 v[132:133], v6 offset1:129
	s_waitcnt lgkmcnt(0)
	v_mul_f32_e32 v2, v2, v70
	v_fma_f32 v3, v3, v70, v102
	v_cvt_pk_bf16_f32 v9, v3, s0
	ds_write_b16 v0, v9 offset:8704
	v_cvt_pk_bf16_f32 v10, v2, s0
	ds_write_b16 v8, v10 offset:8704
	v_mul_f32_e32 v2, v2, v71
	v_fma_f32 v3, v3, v71, v103
	v_cvt_pk_bf16_f32 v11, v3, s0
	ds_write_b16 v0, v11 offset:8976
	v_cvt_pk_bf16_f32 v12, v2, s0
	ds_write_b16 v8, v12 offset:8976
	v_mul_f32_e32 v2, v2, v72
	v_fma_f32 v3, v3, v72, v104
	v_cvt_pk_bf16_f32 v9, v3, s0
	ds_write_b16 v0, v9 offset:9248
	v_cvt_pk_bf16_f32 v10, v2, s0
	ds_write_b16 v8, v10 offset:9248
	v_mul_f32_e32 v2, v2, v73
	v_fma_f32 v3, v3, v73, v105
	v_cvt_pk_bf16_f32 v11, v3, s0
	ds_write_b16 v0, v11 offset:9520
	v_cvt_pk_bf16_f32 v12, v2, s0
	ds_write_b16 v8, v12 offset:9520
	v_mul_f32_e32 v2, v2, v74
	v_fma_f32 v3, v3, v74, v106
	v_cvt_pk_bf16_f32 v9, v3, s0
	ds_write_b16 v0, v9 offset:9792
	v_cvt_pk_bf16_f32 v10, v2, s0
	ds_write_b16 v8, v10 offset:9792
	v_mul_f32_e32 v2, v2, v75
	v_fma_f32 v3, v3, v75, v107
	v_cvt_pk_bf16_f32 v11, v3, s0
	ds_write_b16 v0, v11 offset:10064
	v_cvt_pk_bf16_f32 v12, v2, s0
	ds_write_b16 v8, v12 offset:10064
	v_mul_f32_e32 v2, v2, v76
	v_fma_f32 v3, v3, v76, v108
	v_cvt_pk_bf16_f32 v9, v3, s0
	ds_write_b16 v0, v9 offset:10336
	v_cvt_pk_bf16_f32 v10, v2, s0
	ds_write_b16 v8, v10 offset:10336
	v_mul_f32_e32 v2, v2, v77
	v_fma_f32 v3, v3, v77, v109
	v_cvt_pk_bf16_f32 v11, v3, s0
	ds_write_b16 v0, v11 offset:10608
	v_cvt_pk_bf16_f32 v12, v2, s0
	ds_write_b16 v8, v12 offset:10608
	v_mul_f32_e32 v2, v2, v78
	v_fma_f32 v3, v3, v78, v110
	v_cvt_pk_bf16_f32 v9, v3, s0
	ds_write_b16 v0, v9 offset:10880
	v_cvt_pk_bf16_f32 v10, v2, s0
	ds_write_b16 v8, v10 offset:10880
	v_mul_f32_e32 v2, v2, v79
	v_fma_f32 v3, v3, v79, v111
	v_cvt_pk_bf16_f32 v11, v3, s0
	ds_write_b16 v0, v11 offset:11152
	v_cvt_pk_bf16_f32 v12, v2, s0
	ds_write_b16 v8, v12 offset:11152
	v_mul_f32_e32 v2, v2, v80
	v_fma_f32 v3, v3, v80, v112
	v_cvt_pk_bf16_f32 v9, v3, s0
	ds_write_b16 v0, v9 offset:11424
	v_cvt_pk_bf16_f32 v10, v2, s0
	ds_write_b16 v8, v10 offset:11424
	v_mul_f32_e32 v2, v2, v81
	v_fma_f32 v3, v3, v81, v113
	v_cvt_pk_bf16_f32 v11, v3, s0
	ds_write_b16 v0, v11 offset:11696
	v_cvt_pk_bf16_f32 v12, v2, s0
	ds_write_b16 v8, v12 offset:11696
	v_mul_f32_e32 v2, v2, v82
	v_fma_f32 v3, v3, v82, v114
	v_cvt_pk_bf16_f32 v9, v3, s0
	ds_write_b16 v0, v9 offset:11968
	v_cvt_pk_bf16_f32 v10, v2, s0
	ds_write_b16 v8, v10 offset:11968
	v_mul_f32_e32 v2, v2, v83
	v_fma_f32 v3, v3, v83, v115
	v_cvt_pk_bf16_f32 v11, v3, s0
	ds_write_b16 v0, v11 offset:12240
	v_cvt_pk_bf16_f32 v12, v2, s0
	ds_write_b16 v8, v12 offset:12240
	v_mul_f32_e32 v2, v2, v84
	v_fma_f32 v3, v3, v84, v116
	v_cvt_pk_bf16_f32 v9, v3, s0
	ds_write_b16 v0, v9 offset:12512
	v_cvt_pk_bf16_f32 v10, v2, s0
	ds_write_b16 v8, v10 offset:12512
	v_mul_f32_e32 v2, v2, v85
	v_fma_f32 v3, v3, v85, v117
	v_cvt_pk_bf16_f32 v11, v3, s0
	ds_write_b16 v0, v11 offset:12784
	v_cvt_pk_bf16_f32 v12, v2, s0
	ds_write_b16 v8, v12 offset:12784
	v_mul_f32_e32 v2, v2, v86
	v_fma_f32 v3, v3, v86, v118
	v_cvt_pk_bf16_f32 v9, v3, s0
	ds_write_b16 v0, v9 offset:13056
	v_cvt_pk_bf16_f32 v10, v2, s0
	ds_write_b16 v8, v10 offset:13056
	v_mul_f32_e32 v2, v2, v87
	v_fma_f32 v3, v3, v87, v119
	v_cvt_pk_bf16_f32 v11, v3, s0
	ds_write_b16 v0, v11 offset:13328
	v_cvt_pk_bf16_f32 v12, v2, s0
	ds_write_b16 v8, v12 offset:13328
	v_mul_f32_e32 v2, v2, v88
	v_fma_f32 v3, v3, v88, v120
	v_cvt_pk_bf16_f32 v9, v3, s0
	ds_write_b16 v0, v9 offset:13600
	v_cvt_pk_bf16_f32 v10, v2, s0
	ds_write_b16 v8, v10 offset:13600
	v_mul_f32_e32 v2, v2, v89
	v_fma_f32 v3, v3, v89, v121
	v_cvt_pk_bf16_f32 v11, v3, s0
	ds_write_b16 v0, v11 offset:13872
	v_cvt_pk_bf16_f32 v12, v2, s0
	ds_write_b16 v8, v12 offset:13872
	v_mul_f32_e32 v2, v2, v90
	v_fma_f32 v3, v3, v90, v122
	v_cvt_pk_bf16_f32 v9, v3, s0
	ds_write_b16 v0, v9 offset:14144
	v_cvt_pk_bf16_f32 v10, v2, s0
	ds_write_b16 v8, v10 offset:14144
	v_mul_f32_e32 v2, v2, v91
	v_fma_f32 v3, v3, v91, v123
	v_cvt_pk_bf16_f32 v11, v3, s0
	ds_write_b16 v0, v11 offset:14416
	v_cvt_pk_bf16_f32 v12, v2, s0
	ds_write_b16 v8, v12 offset:14416
	v_mul_f32_e32 v2, v2, v92
	v_fma_f32 v3, v3, v92, v124
	v_cvt_pk_bf16_f32 v9, v3, s0
	ds_write_b16 v0, v9 offset:14688
	v_cvt_pk_bf16_f32 v10, v2, s0
	ds_write_b16 v8, v10 offset:14688
	v_mul_f32_e32 v2, v2, v93
	v_fma_f32 v3, v3, v93, v125
	v_cvt_pk_bf16_f32 v11, v3, s0
	ds_write_b16 v0, v11 offset:14960
	v_cvt_pk_bf16_f32 v12, v2, s0
	ds_write_b16 v8, v12 offset:14960
	v_mul_f32_e32 v2, v2, v94
	v_fma_f32 v3, v3, v94, v126
	v_cvt_pk_bf16_f32 v9, v3, s0
	ds_write_b16 v0, v9 offset:15232
	v_cvt_pk_bf16_f32 v10, v2, s0
	ds_write_b16 v8, v10 offset:15232
	v_mul_f32_e32 v2, v2, v95
	v_fma_f32 v3, v3, v95, v127
	v_cvt_pk_bf16_f32 v11, v3, s0
	ds_write_b16 v0, v11 offset:15504
	v_cvt_pk_bf16_f32 v12, v2, s0
	ds_write_b16 v8, v12 offset:15504
	v_mul_f32_e32 v2, v2, v96
	v_fma_f32 v3, v3, v96, v128
	v_cvt_pk_bf16_f32 v9, v3, s0
	ds_write_b16 v0, v9 offset:15776
	v_cvt_pk_bf16_f32 v10, v2, s0
	ds_write_b16 v8, v10 offset:15776
	v_mul_f32_e32 v2, v2, v97
	v_fma_f32 v3, v3, v97, v129
	v_cvt_pk_bf16_f32 v11, v3, s0
	ds_write_b16 v0, v11 offset:16048
	v_cvt_pk_bf16_f32 v12, v2, s0
	ds_write_b16 v8, v12 offset:16048
	v_mul_f32_e32 v2, v2, v98
	v_fma_f32 v3, v3, v98, v130
	v_cvt_pk_bf16_f32 v9, v3, s0
	ds_write_b16 v0, v9 offset:16320
	v_cvt_pk_bf16_f32 v10, v2, s0
	ds_write_b16 v8, v10 offset:16320
	v_mul_f32_e32 v2, v2, v99
	v_fma_f32 v3, v3, v99, v131
	v_cvt_pk_bf16_f32 v11, v3, s0
	ds_write_b16 v0, v11 offset:16592
	v_cvt_pk_bf16_f32 v12, v2, s0
	ds_write_b16 v8, v12 offset:16592
	v_mul_f32_e32 v2, v2, v100
	v_fma_f32 v3, v3, v100, v132
	v_cvt_pk_bf16_f32 v9, v3, s0
	ds_write_b16 v0, v9 offset:16864
	v_cvt_pk_bf16_f32 v10, v2, s0
	ds_write_b16 v8, v10 offset:16864
	v_mul_f32_e32 v2, v2, v101
	v_fma_f32 v3, v3, v101, v133
	v_cvt_pk_bf16_f32 v11, v3, s0
	ds_write_b16 v0, v11 offset:17136
	v_cvt_pk_bf16_f32 v12, v2, s0
	ds_write_b16 v8, v12 offset:17136
	s_mul_i32 s4, s26, 0x300
	s_add_i32 s4, s4, s68
	v_add_u32_e32 v4, s4, v39
	v_ashrrev_i32_e32 v5, 31, v4
	v_readlane_b32 s4, v249, 34
	v_lshlrev_b64 v[4:5], 2, v[4:5]
	v_readlane_b32 s5, v249, 35
	s_nop 1
	v_lshl_add_u64 v[6:7], s[4:5], 0, v[4:5]
	v_readlane_b32 s4, v249, 36
	v_readlane_b32 s5, v249, 37
	global_store_dword v[6:7], v2, off
	s_nop 0
	v_lshl_add_u64 v[4:5], s[4:5], 0, v[4:5]
	global_store_dword v[4:5], v3, off
